# norm + final rmsnorm row reductions: permlane32/16_swap + DPP butterfly (same pairing order) instead of 6 ds_bpermute round trips
# baseline (speedup 1.0000x reference)
; DI void ph_norm(const Params& p, int l, int bid, int nb) {
;     ...
;   for (int it = bid; it < ROWS / 8; it += nb) {
;     float4 v[2][4];
;     const float* mod[2];
; #pragma unroll
;     for (int rr = 0; rr < 2; ++rr) {
;       const int row = it * 8 + rr * 4 + w;
;       const int b = row / NTOK, t = row % NTOK;
;       const float* src = xsrc_row(p, l, b, t);
;       mod[rr] = MOD + ((size_t)l * 9 + (t < NCTX ? 8 : b)) * 3072;
; #pragma unroll
;       for (int i = 0; i < 4; ++i) v[rr][i] = *(const float4*)(src + (i * 64 + lane) * 4);
;     }
; #pragma unroll
;     for (int rr = 0; rr < 2; ++rr) {
;       const int row = it * 8 + rr * 4 + w;
;       float ss = 0.f;
; #pragma unroll
;       for (int i = 0; i < 4; ++i) ss += v[rr][i].x * v[rr][i].x + v[rr][i].y * v[rr][i].y + v[rr][i].z * v[rr][i].z + v[rr][i].w * v[rr][i].w;
;       ss = wave_sum(ss);
;       const float rstd = rsqrtf(ss * (1.f / DM) + EPS);
.LBB0_115:
	s_or_b64 exec, exec, s[8:9]
	v_lshlrev_b64 v[8:9], v16, v[8:9]
	v_lshl_add_u64 v[8:9], v[18:19], 0, v[8:9]
	v_lshlrev_b64 v[10:11], 12, v[10:11]
	v_lshl_add_u64 v[8:9], v[8:9], 0, v[10:11]
	v_lshl_add_u64 v[8:9], v[8:9], 0, v[46:47]
	global_load_dwordx4 v[28:31], v[8:9], off
	global_load_dwordx4 v[20:23], v[8:9], off offset:1024
	global_load_dwordx4 v[16:19], v[8:9], off offset:2048
	s_nop 0
	global_load_dwordx4 v[8:11], v[8:9], off offset:3072
	v_add_u32_e32 v45, s2, v58
	s_waitcnt vmcnt(0) lgkmcnt(0)
	v_mov_b32_e32 v70, v25
	v_mov_b32_e32 v71, v13
	v_mov_b32_e32 v58, v24
	v_mov_b32_e32 v59, v12
	v_mov_b32_e32 v78, v5
	v_mov_b32_e32 v79, v1
	v_mul_hi_i32_i24_e32 v85, 0x3000, v45
	v_mul_i32_i24_e32 v84, 0x3000, v45
	v_pk_mul_f32 v[70:71], v[70:71], v[70:71]
	v_mov_b32_e32 v72, v26
	v_mov_b32_e32 v73, v14
	v_mov_b32_e32 v76, v4
	v_mov_b32_e32 v77, v0
	v_pk_mul_f32 v[78:79], v[78:79], v[78:79]
	v_lshl_add_u64 v[84:85], s[0:1], 0, v[84:85]
	v_pk_fma_f32 v[58:59], v[58:59], v[58:59], v[70:71]
	s_mov_b64 s[12:13], 0x1000
	v_mov_b32_e32 v74, v27
	v_mov_b32_e32 v75, v15
	v_mov_b32_e32 v80, v6
	v_mov_b32_e32 v81, v2
	v_pk_fma_f32 v[70:71], v[76:77], v[76:77], v[78:79]
	v_pk_fma_f32 v[58:59], v[72:73], v[72:73], v[58:59]
	v_lshl_add_u64 v[78:79], v[84:85], 0, s[12:13]
	v_mov_b32_e32 v82, v7
	v_mov_b32_e32 v83, v3
	v_pk_fma_f32 v[70:71], v[80:81], v[80:81], v[70:71]
	v_lshl_add_u64 v[80:81], v[84:85], 0, v[46:47]
	v_pk_fma_f32 v[58:59], v[74:75], v[74:75], v[58:59]
	v_lshl_add_u64 v[74:75], v[78:79], 0, v[46:47]
	global_load_dwordx4 v[66:69], v[34:35], off
	v_pk_fma_f32 v[82:83], v[82:83], v[82:83], v[70:71]
	global_load_dwordx4 v[70:73], v[80:81], off
	s_nop 0
	global_load_dwordx4 v[74:77], v[74:75], off
	v_mov_b32_e32 v85, v58
	v_mov_b32_e32 v87, v82
	s_mov_b32 s8, 0x3a800000
	v_ashrrev_i32_e32 v45, 31, v44
	s_add_i32 s10, s10, s54
	s_mov_b32 s38, 0x800000
	s_cmpk_lt_i32 s10, 0x900
	v_mov_b32_e32 v94, v29
	v_mov_b32_e32 v95, v21
	v_mov_b32_e32 v92, v28
	v_mov_b32_e32 v93, v20
	v_mov_b32_e32 v102, v17
	v_mov_b32_e32 v103, v9
	v_pk_mul_f32 v[94:95], v[94:95], v[94:95]
	v_mov_b32_e32 v88, v30
	v_mov_b32_e32 v89, v22
	v_mov_b32_e32 v100, v16
	v_mov_b32_e32 v101, v8
	v_pk_mul_f32 v[102:103], v[102:103], v[102:103]
	v_pk_fma_f32 v[92:93], v[92:93], v[92:93], v[94:95]
	v_mov_b32_e32 v90, v31
	v_mov_b32_e32 v91, v23
	v_mov_b32_e32 v96, v18
	v_mov_b32_e32 v97, v10
	v_pk_fma_f32 v[94:95], v[100:101], v[100:101], v[102:103]
	v_pk_fma_f32 v[88:89], v[88:89], v[88:89], v[92:93]
	v_mov_b32_e32 v98, v19
	v_mov_b32_e32 v99, v11
	v_pk_fma_f32 v[92:93], v[96:97], v[96:97], v[94:95]
	v_pk_fma_f32 v[88:89], v[90:91], v[90:91], v[88:89]
	v_pk_fma_f32 v[90:91], v[98:99], v[98:99], v[92:93]
	v_mov_b32_e32 v84, v88
	v_mov_b32_e32 v58, v89
	v_mov_b32_e32 v86, v90
	v_pk_add_f32 v[58:59], v[84:85], v[58:59]
	v_mov_b32_e32 v82, v91
	v_pk_add_f32 v[58:59], v[58:59], v[86:87]
	v_lshl_add_u64 v[84:85], v[44:45], 0, v[36:37]
	v_pk_add_f32 v[58:59], v[58:59], v[82:83]
	v_mov_b32_e32 v82, v58
	v_mov_b32_e32 v83, v59
	v_lshlrev_b64 v[84:85], 6, v[84:85]
	v_lshl_add_u64 v[84:85], v[32:33], 0, v[84:85]
	v_permlane32_swap_b32_e32 v82, v58
	v_permlane32_swap_b32_e32 v83, v59
	v_pk_add_f32 v[58:59], v[58:59], v[82:83]
	v_mov_b32_e32 v82, v58
	v_mov_b32_e32 v83, v59
	s_nop 1
	v_permlane16_swap_b32_e32 v82, v58
	v_permlane16_swap_b32_e32 v83, v59
	v_pk_add_f32 v[58:59], v[58:59], v[82:83]
	s_nop 1
	v_add_f32_dpp v58, v58, v58 row_ror:8 row_mask:0xf bank_mask:0xf
	v_add_f32_dpp v59, v59, v59 row_ror:8 row_mask:0xf bank_mask:0xf
	s_nop 0
	v_add_f32_dpp v82, v58, v58 row_shl:4 row_mask:0xf bank_mask:0x5
	v_add_f32_dpp v83, v59, v59 row_shl:4 row_mask:0xf bank_mask:0x5
	v_add_f32_dpp v82, v58, v58 row_shr:4 row_mask:0xf bank_mask:0xa
	v_add_f32_dpp v83, v59, v59 row_shr:4 row_mask:0xf bank_mask:0xa
	s_nop 0
	v_add_f32_dpp v58, v82, v82 quad_perm:[2,3,0,1] row_mask:0xf bank_mask:0xf
	v_add_f32_dpp v59, v83, v83 quad_perm:[2,3,0,1] row_mask:0xf bank_mask:0xf
	s_nop 0
	v_add_f32_dpp v58, v58, v58 quad_perm:[1,0,3,2] row_mask:0xf bank_mask:0xf
	v_add_f32_dpp v59, v59, v59 quad_perm:[1,0,3,2] row_mask:0xf bank_mask:0xf
	s_waitcnt vmcnt(0)
	v_pk_add_f32 v[74:75], v[74:75], 1.0 op_sel_hi:[1,0]
	v_pk_add_f32 v[76:77], v[76:77], 1.0 op_sel_hi:[1,0]
	s_nop 0
	v_pk_fma_f32 v[58:59], v[58:59], s[8:9], v[162:163] op_sel_hi:[1,0,0]
	s_mov_b32 s8, 0x800000
	v_mul_f32_e32 v55, 0x4b800000, v59
	v_cmp_gt_f32_e32 vcc, s8, v59
	v_lshl_add_u64 v[82:83], v[78:79], 0, v[48:49]
	s_nop 0
	v_cndmask_b32_e32 v55, v59, v55, vcc
	v_rsq_f32_e32 v55, v55
	s_nop 0
	v_mul_f32_e32 v57, 0x45800000, v55
	v_cndmask_b32_e32 v86, v55, v57, vcc
	v_pk_mul_f32 v[24:25], v[24:25], v[86:87] op_sel_hi:[1,0]
	v_pk_mul_f32 v[26:27], v[26:27], v[86:87] op_sel_hi:[1,0]
	v_pk_mul_f32 v[24:25], v[66:67], v[24:25]
	v_pk_mul_f32 v[26:27], v[68:69], v[26:27]
	v_pk_fma_f32 v[24:25], v[74:75], v[24:25], v[70:71]
	v_pk_fma_f32 v[26:27], v[26:27], v[76:77], v[72:73]
	v_cvt_pk_bf16_f32 v24, v24, v25
	v_cvt_pk_bf16_f32 v25, v26, v27
	global_store_dwordx2 v[84:85], v[24:25], off
	global_load_dwordx4 v[24:27], v[34:35], off offset:1024
	s_nop 0
	global_load_dwordx4 v[66:69], v[82:83], off
	global_load_dwordx4 v[70:73], v[80:81], off offset:1024
	v_pk_mul_f32 v[12:13], v[12:13], v[86:87] op_sel_hi:[1,0]
	v_pk_mul_f32 v[14:15], v[14:15], v[86:87] op_sel_hi:[1,0]
	v_lshl_add_u64 v[74:75], v[44:45], 0, v[38:39]
	v_lshlrev_b64 v[74:75], 6, v[74:75]
	v_lshl_add_u64 v[74:75], v[32:33], 0, v[74:75]
	v_lshl_add_u64 v[76:77], v[78:79], 0, v[50:51]
	v_pk_mul_f32 v[4:5], v[4:5], v[86:87] op_sel_hi:[1,0]
	v_pk_mul_f32 v[6:7], v[6:7], v[86:87] op_sel_hi:[1,0]
	v_pk_mul_f32 v[0:1], v[0:1], v[86:87] op_sel_hi:[1,0]
	v_pk_mul_f32 v[2:3], v[2:3], v[86:87] op_sel_hi:[1,0]
	v_add_u32_e32 v55, s2, v56
	v_mul_hi_i32_i24_e32 v57, 0x3000, v55
	v_mul_i32_i24_e32 v56, 0x3000, v55
	v_lshl_add_u64 v[56:57], s[0:1], 0, v[56:57]
	v_cmp_gt_f32_e32 vcc, s8, v58
	v_ashrrev_i32_e32 v55, 31, v54
	v_readlane_b32 s8, v254, 11
	s_waitcnt vmcnt(0)
; DI size_t kblk(int row, int col, int nrows) { return ((size_t)(col >> 5) * nrows + row) * 32 + (col & 31); }
; DI unsigned pk2(float a, float b) { hwf32x2 f = {a, b}; hwbf16x2 r = __builtin_convertvector(f, hwbf16x2); return __builtin_bit_cast(unsigned, r); }
; DI void ph_norm(const Params& p, int l, int bid, int nb) {
;     ...
; #pragma unroll
;       for (int i = 0; i < 4; ++i) {
;         const int j = (i * 64 + lane) * 4;
;         const float4 gg = *(const float4*)(g + j);
;         const float4 sh = *(const float4*)(mod[rr] + j);
;         const float4 sc = *(const float4*)(mod[rr] + 1024 + j);
;         uint2 o;
;         o.x = pk2(v[rr][i].x * rstd * gg.x * (1.f + sc.x) + sh.x, v[rr][i].y * rstd * gg.y * (1.f + sc.y) + sh.y);
;         o.y = pk2(v[rr][i].z * rstd * gg.z * (1.f + sc.z) + sh.z, v[rr][i].w * rstd * gg.w * (1.f + sc.w) + sh.w);
;         *(uint2*)(H + kblk(row, j, ROWS)) = o;
;       }
;     }
	v_pk_mul_f32 v[12:13], v[12:13], v[24:25]
	s_waitcnt lgkmcnt(0)
	v_pk_add_f32 v[24:25], v[66:67], 1.0 op_sel_hi:[1,0]
	v_pk_mul_f32 v[14:15], v[14:15], v[26:27]
	v_pk_add_f32 v[26:27], v[68:69], 1.0 op_sel_hi:[1,0]
	v_pk_fma_f32 v[12:13], v[12:13], v[24:25], v[70:71]
	v_pk_fma_f32 v[14:15], v[14:15], v[26:27], v[72:73]
	v_cvt_pk_bf16_f32 v12, v12, v13
	v_cvt_pk_bf16_f32 v13, v14, v15
	global_store_dwordx2 v[74:75], v[12:13], off
	global_load_dwordx4 v[12:15], v[34:35], off offset:2048
	s_nop 0
	global_load_dwordx4 v[24:27], v[76:77], off
	global_load_dwordx4 v[66:69], v[80:81], off offset:2048
	v_lshl_add_u64 v[70:71], v[44:45], 0, v[40:41]
	v_lshlrev_b64 v[70:71], 6, v[70:71]
	v_lshl_add_u64 v[70:71], v[32:33], 0, v[70:71]
	v_lshl_add_u64 v[72:73], v[78:79], 0, v[52:53]
	s_waitcnt vmcnt(0)
	v_pk_mul_f32 v[4:5], v[4:5], v[12:13]
	s_waitcnt lgkmcnt(0)
	v_pk_add_f32 v[12:13], v[24:25], 1.0 op_sel_hi:[1,0]
	v_pk_mul_f32 v[6:7], v[6:7], v[14:15]
	v_pk_add_f32 v[14:15], v[26:27], 1.0 op_sel_hi:[1,0]
	v_pk_fma_f32 v[4:5], v[4:5], v[12:13], v[66:67]
	v_pk_fma_f32 v[6:7], v[6:7], v[14:15], v[68:69]
	v_cvt_pk_bf16_f32 v4, v4, v5
	v_cvt_pk_bf16_f32 v5, v6, v7
	global_store_dwordx2 v[70:71], v[4:5], off
	global_load_dwordx4 v[4:7], v[34:35], off offset:3072
	s_nop 0
	global_load_dwordx4 v[12:15], v[72:73], off
	global_load_dwordx4 v[24:27], v[80:81], off offset:3072
	v_lshl_add_u64 v[66:67], v[44:45], 0, v[42:43]
	v_lshlrev_b64 v[66:67], 6, v[66:67]
	v_lshl_add_u64 v[66:67], v[32:33], 0, v[66:67]
	v_lshl_add_u64 v[68:69], v[56:57], 0, s[12:13]
	v_lshl_add_u64 v[70:71], v[68:69], 0, v[46:47]
	v_mul_f32_e32 v45, 0x4b800000, v58
	v_cndmask_b32_e32 v45, v58, v45, vcc
	v_rsq_f32_e32 v45, v45
	v_add_u32_e32 v44, s8, v44
	v_mul_f32_e32 v58, 0x45800000, v45
	v_cndmask_b32_e32 v58, v45, v58, vcc
	v_pk_mul_f32 v[28:29], v[28:29], v[58:59] op_sel_hi:[1,0]
	v_pk_mul_f32 v[30:31], v[30:31], v[58:59] op_sel_hi:[1,0]
	v_pk_mul_f32 v[20:21], v[20:21], v[58:59] op_sel_hi:[1,0]
	v_pk_mul_f32 v[22:23], v[22:23], v[58:59] op_sel_hi:[1,0]
	v_pk_mul_f32 v[16:17], v[16:17], v[58:59] op_sel_hi:[1,0]
	v_pk_mul_f32 v[18:19], v[18:19], v[58:59] op_sel_hi:[1,0]
	v_pk_mul_f32 v[8:9], v[8:9], v[58:59] op_sel_hi:[1,0]
	v_pk_mul_f32 v[10:11], v[10:11], v[58:59] op_sel_hi:[1,0]
	s_waitcnt vmcnt(0)
	v_pk_mul_f32 v[0:1], v[0:1], v[4:5]
	s_waitcnt lgkmcnt(0)
	v_pk_add_f32 v[4:5], v[12:13], 1.0 op_sel_hi:[1,0]
	v_pk_mul_f32 v[2:3], v[2:3], v[6:7]
	v_pk_add_f32 v[6:7], v[14:15], 1.0 op_sel_hi:[1,0]
	v_pk_fma_f32 v[0:1], v[0:1], v[4:5], v[24:25]
	v_pk_fma_f32 v[2:3], v[2:3], v[6:7], v[26:27]
	v_cvt_pk_bf16_f32 v0, v0, v1
	v_cvt_pk_bf16_f32 v1, v2, v3
	global_store_dwordx2 v[66:67], v[0:1], off
	global_load_dwordx4 v[0:3], v[34:35], off
	s_nop 0
	global_load_dwordx4 v[4:7], v[70:71], off
	v_lshl_add_u64 v[24:25], v[56:57], 0, v[46:47]
	global_load_dwordx4 v[12:15], v[24:25], off
	v_lshl_add_u64 v[26:27], v[54:55], 0, v[36:37]
	v_lshlrev_b64 v[26:27], 6, v[26:27]
	v_lshl_add_u64 v[26:27], v[32:33], 0, v[26:27]
	v_lshl_add_u64 v[56:57], v[68:69], 0, v[48:49]
	s_waitcnt vmcnt(0)
	v_pk_mul_f32 v[0:1], v[0:1], v[28:29]
	s_waitcnt lgkmcnt(0)
	v_pk_add_f32 v[4:5], v[4:5], 1.0 op_sel_hi:[1,0]
	v_pk_mul_f32 v[2:3], v[2:3], v[30:31]
	v_pk_add_f32 v[6:7], v[6:7], 1.0 op_sel_hi:[1,0]
	v_pk_fma_f32 v[0:1], v[4:5], v[0:1], v[12:13]
	v_pk_fma_f32 v[2:3], v[2:3], v[6:7], v[14:15]
	v_cvt_pk_bf16_f32 v0, v0, v1
	v_cvt_pk_bf16_f32 v1, v2, v3
	global_store_dwordx2 v[26:27], v[0:1], off
	global_load_dwordx4 v[0:3], v[34:35], off offset:1024
	s_nop 0
	global_load_dwordx4 v[4:7], v[56:57], off
	global_load_dwordx4 v[12:15], v[24:25], off offset:1024
	v_lshl_add_u64 v[26:27], v[54:55], 0, v[38:39]
	v_lshlrev_b64 v[26:27], 6, v[26:27]
	v_lshl_add_u64 v[26:27], v[32:33], 0, v[26:27]
	v_lshl_add_u64 v[28:29], v[68:69], 0, v[50:51]
	s_waitcnt vmcnt(0)
	v_pk_mul_f32 v[0:1], v[20:21], v[0:1]
	s_waitcnt lgkmcnt(0)
	v_pk_add_f32 v[4:5], v[4:5], 1.0 op_sel_hi:[1,0]
	v_pk_mul_f32 v[2:3], v[22:23], v[2:3]
	v_pk_add_f32 v[6:7], v[6:7], 1.0 op_sel_hi:[1,0]
	v_pk_fma_f32 v[0:1], v[0:1], v[4:5], v[12:13]
	v_pk_fma_f32 v[2:3], v[2:3], v[6:7], v[14:15]
	v_cvt_pk_bf16_f32 v0, v0, v1
	v_cvt_pk_bf16_f32 v1, v2, v3
	global_store_dwordx2 v[26:27], v[0:1], off
	global_load_dwordx4 v[0:3], v[34:35], off offset:2048
	s_nop 0
	global_load_dwordx4 v[4:7], v[28:29], off
	global_load_dwordx4 v[12:15], v[24:25], off offset:2048
	v_lshl_add_u64 v[20:21], v[54:55], 0, v[40:41]
	v_lshlrev_b64 v[20:21], 6, v[20:21]
	v_lshl_add_u64 v[20:21], v[32:33], 0, v[20:21]
	v_lshl_add_u64 v[22:23], v[68:69], 0, v[52:53]
	s_waitcnt vmcnt(0)
	v_pk_mul_f32 v[0:1], v[16:17], v[0:1]
	s_waitcnt lgkmcnt(0)
	v_pk_add_f32 v[4:5], v[4:5], 1.0 op_sel_hi:[1,0]
	v_pk_mul_f32 v[2:3], v[18:19], v[2:3]
	v_pk_add_f32 v[6:7], v[6:7], 1.0 op_sel_hi:[1,0]
	v_pk_fma_f32 v[0:1], v[0:1], v[4:5], v[12:13]
	v_pk_fma_f32 v[2:3], v[2:3], v[6:7], v[14:15]
	v_cvt_pk_bf16_f32 v0, v0, v1
	v_cvt_pk_bf16_f32 v1, v2, v3
	global_store_dwordx2 v[20:21], v[0:1], off
	global_load_dwordx4 v[0:3], v[34:35], off offset:3072
	s_nop 0
	global_load_dwordx4 v[4:7], v[22:23], off
	global_load_dwordx4 v[12:15], v[24:25], off offset:3072
	v_lshl_add_u64 v[16:17], v[54:55], 0, v[42:43]
	v_lshlrev_b64 v[16:17], 6, v[16:17]
	v_lshl_add_u64 v[16:17], v[32:33], 0, v[16:17]
	s_waitcnt vmcnt(0)
	v_pk_mul_f32 v[0:1], v[8:9], v[0:1]
	s_waitcnt lgkmcnt(0)
	v_pk_add_f32 v[4:5], v[4:5], 1.0 op_sel_hi:[1,0]
	v_pk_mul_f32 v[2:3], v[10:11], v[2:3]
	v_pk_add_f32 v[6:7], v[6:7], 1.0 op_sel_hi:[1,0]
	v_pk_fma_f32 v[0:1], v[0:1], v[4:5], v[12:13]
	v_pk_fma_f32 v[2:3], v[2:3], v[6:7], v[14:15]
	v_cvt_pk_bf16_f32 v0, v0, v1
	v_cvt_pk_bf16_f32 v1, v2, v3
	global_store_dwordx2 v[16:17], v[0:1], off
	s_cbranch_scc0 .LBB0_124

; DI void ph_final(const Params& p, int bid, int nb) {
;     ...
; #pragma unroll
;     for (int rr = 0; rr < 2; ++rr) {
;       float* rp = p.out + (size_t)(it * 8 + rr * 4 + w) * DM;
;       float ss = 0.f;
; #pragma unroll
;       for (int i = 0; i < 4; ++i) ss += v[rr][i].x * v[rr][i].x + v[rr][i].y * v[rr][i].y + v[rr][i].z * v[rr][i].z + v[rr][i].w * v[rr][i].w;
;       ss = wave_sum(ss);
;       const float rstd = rsqrtf(ss * (1.f / DM) + EPS);
; #pragma unroll
;       for (int i = 0; i < 4; ++i) {
;         const int j = (i * 64 + lane) * 4;
;         const float4 gg = *(const float4*)(p.final_g + j);
;         float4 o;
;         o.x = v[rr][i].x * rstd * gg.x; o.y = v[rr][i].y * rstd * gg.y; o.z = v[rr][i].z * rstd * gg.z; o.w = v[rr][i].w * rstd * gg.w;
;         {
;           typedef float f32x4_t __attribute__((ext_vector_type(4)));
;           const f32x4_t ov = {o.x, o.y, o.z, o.w};
;           __builtin_nontemporal_store(ov, (f32x4_t*)(rp + j));
;         }
;       }
.Lfn_nopf:
	v_mov_b32_e32 v56, v17
	v_mov_b32_e32 v57, v21
	v_mov_b32_e32 v64, v25
	v_mov_b32_e32 v65, v29
	v_mov_b32_e32 v54, v16
	v_mov_b32_e32 v55, v20
	v_mov_b32_e32 v62, v24
	v_mov_b32_e32 v63, v28
	v_pk_mul_f32 v[56:57], v[56:57], v[56:57]
	v_pk_mul_f32 v[64:65], v[64:65], v[64:65]
	v_mov_b32_e32 v72, v33
	v_mov_b32_e32 v73, v37
	v_mov_b32_e32 v58, v18
	v_mov_b32_e32 v59, v22
	v_mov_b32_e32 v70, v32
	v_mov_b32_e32 v71, v36
	v_mov_b32_e32 v80, v41
	v_mov_b32_e32 v81, v45
	v_pk_fma_f32 v[54:55], v[54:55], v[54:55], v[56:57]
	v_pk_fma_f32 v[56:57], v[62:63], v[62:63], v[64:65]
	v_pk_mul_f32 v[62:63], v[72:73], v[72:73]
	v_mov_b32_e32 v74, v34
	v_mov_b32_e32 v75, v38
	v_mov_b32_e32 v78, v40
	v_mov_b32_e32 v79, v44
	v_pk_mul_f32 v[64:65], v[80:81], v[80:81]
	v_pk_fma_f32 v[54:55], v[58:59], v[58:59], v[54:55]
	v_pk_fma_f32 v[58:59], v[70:71], v[70:71], v[62:63]
	v_mov_b32_e32 v60, v19
	v_mov_b32_e32 v61, v23
	v_mov_b32_e32 v66, v26
	v_mov_b32_e32 v67, v30
	v_mov_b32_e32 v76, v35
	v_mov_b32_e32 v77, v39
	v_mov_b32_e32 v82, v42
	v_mov_b32_e32 v83, v46
	v_pk_fma_f32 v[62:63], v[78:79], v[78:79], v[64:65]
	v_pk_fma_f32 v[58:59], v[74:75], v[74:75], v[58:59]
	v_mov_b32_e32 v68, v27
	v_mov_b32_e32 v69, v31
	v_mov_b32_e32 v84, v43
	v_mov_b32_e32 v85, v47
	v_pk_fma_f32 v[56:57], v[66:67], v[66:67], v[56:57]
	v_pk_fma_f32 v[54:55], v[60:61], v[60:61], v[54:55]
	v_pk_fma_f32 v[60:61], v[82:83], v[82:83], v[62:63]
	v_pk_fma_f32 v[58:59], v[76:77], v[76:77], v[58:59]
	v_pk_fma_f32 v[56:57], v[68:69], v[68:69], v[56:57]
	v_pk_fma_f32 v[60:61], v[84:85], v[84:85], v[60:61]
	v_mov_b32_e32 v63, v54
	v_mov_b32_e32 v62, v58
	v_mov_b32_e32 v54, v59
	v_mov_b32_e32 v65, v56
	v_mov_b32_e32 v64, v60
	v_pk_add_f32 v[54:55], v[62:63], v[54:55]
	v_mov_b32_e32 v56, v61
	v_pk_add_f32 v[54:55], v[54:55], v[64:65]
	s_nop 0
	v_pk_add_f32 v[54:55], v[54:55], v[56:57]
	v_mov_b32_e32 v56, v54
	v_mov_b32_e32 v57, v55
	s_nop 1
	v_permlane32_swap_b32_e32 v56, v54
	v_permlane32_swap_b32_e32 v57, v55
	v_pk_add_f32 v[54:55], v[54:55], v[56:57]
	v_mov_b32_e32 v56, v54
	v_mov_b32_e32 v57, v55
	s_nop 1
	v_permlane16_swap_b32_e32 v56, v54
	v_permlane16_swap_b32_e32 v57, v55
	v_pk_add_f32 v[54:55], v[54:55], v[56:57]
	s_nop 1
	v_add_f32_dpp v54, v54, v54 row_ror:8 row_mask:0xf bank_mask:0xf
	v_add_f32_dpp v55, v55, v55 row_ror:8 row_mask:0xf bank_mask:0xf
	s_nop 0
	v_add_f32_dpp v56, v54, v54 row_shl:4 row_mask:0xf bank_mask:0x5
	v_add_f32_dpp v57, v55, v55 row_shl:4 row_mask:0xf bank_mask:0x5
	v_add_f32_dpp v56, v54, v54 row_shr:4 row_mask:0xf bank_mask:0xa
	v_add_f32_dpp v57, v55, v55 row_shr:4 row_mask:0xf bank_mask:0xa
	s_nop 0
	v_add_f32_dpp v54, v56, v56 quad_perm:[2,3,0,1] row_mask:0xf bank_mask:0xf
	v_add_f32_dpp v55, v57, v57 quad_perm:[2,3,0,1] row_mask:0xf bank_mask:0xf
	s_nop 0
	v_add_f32_dpp v54, v54, v54 quad_perm:[1,0,3,2] row_mask:0xf bank_mask:0xf
	v_add_f32_dpp v55, v55, v55 quad_perm:[1,0,3,2] row_mask:0xf bank_mask:0xf
	s_nop 0
	v_pk_fma_f32 v[54:55], v[54:55], s[0:1], v[6:7] op_sel_hi:[1,0,0]
	s_nop 0
	v_mul_f32_e32 v5, 0x4b800000, v55
	v_cmp_gt_f32_e32 vcc, s1, v55
	s_nop 1
	v_cndmask_b32_e32 v5, v55, v5, vcc
	v_rsq_f32_e32 v5, v5
	s_nop 0
	v_mul_f32_e32 v15, 0x45800000, v5
	v_cndmask_b32_e32 v56, v5, v15, vcc
	v_pk_mul_f32 v[16:17], v[16:17], v[56:57] op_sel_hi:[1,0]
	v_pk_mul_f32 v[18:19], v[18:19], v[56:57] op_sel_hi:[1,0]
	v_pk_mul_f32 v[16:17], v[86:87], v[16:17]
	v_pk_mul_f32 v[18:19], v[88:89], v[18:19]
	global_store_dwordx4 v[52:53], v[16:19], off nt
	v_pk_mul_f32 v[22:23], v[22:23], v[56:57] op_sel_hi:[1,0]
	v_pk_mul_f32 v[20:21], v[20:21], v[56:57] op_sel_hi:[1,0]
	v_mul_f32_e32 v5, 0x4b800000, v54
	v_cmp_gt_f32_e32 vcc, s1, v54
	v_pk_mul_f32 v[16:17], v[90:91], v[20:21]
	v_pk_mul_f32 v[18:19], v[92:93], v[22:23]
	global_store_dwordx4 v[52:53], v[16:19], off offset:1024 nt
	v_pk_mul_f32 v[20:21], v[26:27], v[56:57] op_sel_hi:[1,0]
	v_pk_mul_f32 v[22:23], v[24:25], v[56:57] op_sel_hi:[1,0]
	v_cndmask_b32_e32 v5, v54, v5, vcc
	v_rsq_f32_e32 v5, v5
	v_pk_mul_f32 v[16:17], v[22:23], v[94:95]
	v_pk_mul_f32 v[18:19], v[20:21], v[96:97]
	global_store_dwordx4 v[52:53], v[16:19], off offset:2048 nt
	v_pk_mul_f32 v[20:21], v[30:31], v[56:57] op_sel_hi:[1,0]
	v_pk_mul_f32 v[22:23], v[28:29], v[56:57] op_sel_hi:[1,0]
	v_mul_f32_e32 v15, 0x45800000, v5
	v_pk_mul_f32 v[16:17], v[22:23], v[98:99]
	v_pk_mul_f32 v[18:19], v[20:21], v[100:101]
	global_store_dwordx4 v[52:53], v[16:19], off offset:3072 nt
	v_cndmask_b32_e32 v20, v5, v15, vcc
	v_pk_mul_f32 v[22:23], v[34:35], v[20:21] op_sel_hi:[1,0]
	v_pk_mul_f32 v[24:25], v[32:33], v[20:21] op_sel_hi:[1,0]
	v_pk_mul_f32 v[18:19], v[88:89], v[22:23]
	v_pk_mul_f32 v[16:17], v[86:87], v[24:25]
	global_store_dwordx4 v[8:9], v[16:19], off nt
	v_pk_mul_f32 v[22:23], v[38:39], v[20:21] op_sel_hi:[1,0]
	v_pk_mul_f32 v[24:25], v[36:37], v[20:21] op_sel_hi:[1,0]
	v_pk_mul_f32 v[18:19], v[92:93], v[22:23]
	v_pk_mul_f32 v[16:17], v[90:91], v[24:25]
	global_store_dwordx4 v[8:9], v[16:19], off offset:1024 nt
	v_pk_mul_f32 v[22:23], v[42:43], v[20:21] op_sel_hi:[1,0]
	v_pk_mul_f32 v[24:25], v[40:41], v[20:21] op_sel_hi:[1,0]
	v_pk_mul_f32 v[18:19], v[22:23], v[96:97]
	v_pk_mul_f32 v[16:17], v[24:25], v[94:95]
	global_store_dwordx4 v[8:9], v[16:19], off offset:2048 nt
	v_pk_mul_f32 v[22:23], v[46:47], v[20:21] op_sel_hi:[1,0]
	v_pk_mul_f32 v[20:21], v[44:45], v[20:21] op_sel_hi:[1,0]
	v_pk_mul_f32 v[18:19], v[22:23], v[100:101]
	v_pk_mul_f32 v[16:17], v[20:21], v[98:99]
	global_store_dwordx4 v[8:9], v[16:19], off offset:3072 nt
	s_cbranch_scc1 .LBB0_1133
